# prenorm loop: g/scale loads hoisted next to x loads (one wait), b-row loads no longer gated on a-row data
# baseline (speedup 1.0000x reference)
; __device__ __forceinline__ void prenorm_rows(const float* src0, const float* src1, int row_lo, int row_hi, const float* g, const float* scale, float* SS, bf16_t* HB) {
;     ...
;     for (int row = row_lo + gw; row < row_hi; row += 2 * NGW) {
;         const int rowb = row + NGW; const bool hasb = rowb < row_hi; const int rb = hasb ? rowb : row;
;         const float* srca = row < NTOK ? src0 + (size_t)row * D : src1 + (size_t)(row - NTOK) * D;
;         const float* srcb = rb < NTOK ? src0 + (size_t)rb * D : src1 + (size_t)(rb - NTOK) * D;
;         const int mba = row < NTOK ? (row >> 12) : 4, mbb = rb < NTOK ? (rb >> 12) : 4;
;         const f32x4* xa = (const f32x4*)srca + lane; const f32x4* xb = (const f32x4*)srcb + lane;
;         f32x4 va[4], vb[4]; float sa = 0.f, sb = 0.f;
; #pragma unroll
;         for (int j = 0; j < 4; ++j) { va[j] = xa[64 * j]; vb[j] = xb[64 * j]; }
; #pragma unroll
;         for (int j = 0; j < 4; ++j) { sa += (va[j][0] * va[j][0] + va[j][1] * va[j][1]) + (va[j][2] * va[j][2] + va[j][3] * va[j][3]); sb += (vb[j][0] * vb[j][0] + vb[j][1] * vb[j][1]) + (vb[j][2] * vb[j][2] + vb[j][3] * vb[j][3]); }
;         sa = wave_sum(sa); sb = wave_sum(sb);
;         if (lane == 0) { SS[row] = sa; if (hasb) SS[rowb] = sb; }
;         const f32x4* gp = (const f32x4*)g + lane;
;         const f32x4* sca = (const f32x4*)(scale + (size_t)mba * 9216) + lane; const f32x4* scb = (const f32x4*)(scale + (size_t)mbb * 9216) + lane;
.LBB0_137:
	v_add_u32_e32 v0, 0xffffc000, v48
	v_ashrrev_i32_e32 v49, 31, v48
	v_cmp_gt_i32_e64 s[0:1], s26, v48
	v_add_u32_e32 v66, s94, v48
	s_nop 0
	v_cndmask_b32_e64 v1, 0, v49, s[0:1]
	v_cndmask_b32_e64 v0, v0, v48, s[0:1]
	v_cndmask_b32_e64 v3, v62, v63, s[0:1]
	v_cndmask_b32_e64 v2, v64, v65, s[0:1]
	v_lshlrev_b64 v[0:1], 12, v[0:1]
	v_lshl_add_u64 v[0:1], v[2:3], 0, v[0:1]
	v_cmp_gt_i32_e64 s[0:1], s19, v66
	v_lshl_add_u64 v[0:1], v[0:1], 0, v[46:47]
	global_load_dwordx4 v[28:31], v[0:1], off nt
	v_cndmask_b32_e64 v50, v48, v66, s[0:1]
	global_load_dwordx4 v[20:23], v[0:1], off offset:1024 nt
	global_load_dwordx4 v[12:15], v[0:1], off offset:2048 nt
	global_load_dwordx4 v[4:7], v[0:1], off offset:3072 nt
	v_add_u32_e32 v0, 0xffffc000, v50
	v_ashrrev_i32_e32 v51, 31, v50
	v_cmp_gt_i32_e64 s[12:13], s26, v50
	s_nop 1
	v_cndmask_b32_e64 v1, 0, v51, s[12:13]
	v_cndmask_b32_e64 v0, v0, v50, s[12:13]
	v_cndmask_b32_e64 v3, v62, v63, s[12:13]
	v_cndmask_b32_e64 v2, v64, v65, s[12:13]
	v_lshlrev_b64 v[0:1], 12, v[0:1]
	v_lshl_add_u64 v[0:1], v[2:3], 0, v[0:1]
	v_lshl_add_u64 v[0:1], v[0:1], 0, v[46:47]
	global_load_dwordx4 v[24:27], v[0:1], off nt
	global_load_dwordx4 v[16:19], v[0:1], off offset:1024 nt
	global_load_dwordx4 v[8:11], v[0:1], off offset:2048 nt
	s_nop 0
	global_load_dwordx4 v[0:3], v[0:1], off offset:3072 nt
	v_min_i32_e32 v132, 0x4000, v48
	v_ashrrev_i32_e32 v132, 12, v132
	v_mul_hi_i32_i24_e32 v135, 0x9000, v132
	v_mul_i32_i24_e32 v134, 0x9000, v132
	v_lshl_add_u64 v[128:129], v[42:43], 0, v[134:135]
	v_min_i32_e32 v133, 0x4000, v50
	v_ashrrev_i32_e32 v133, 12, v133
	v_mul_hi_i32_i24_e32 v135, 0x9000, v133
	v_mul_i32_i24_e32 v134, 0x9000, v133
	v_lshl_add_u64 v[130:131], v[42:43], 0, v[134:135]
	global_load_dwordx4 v[80:83], v[40:41], off
	global_load_dwordx4 v[96:99], v[128:129], off
	global_load_dwordx4 v[112:115], v[130:131], off
	global_load_dwordx4 v[84:87], v[40:41], off offset:1024
	global_load_dwordx4 v[100:103], v[128:129], off offset:1024
	global_load_dwordx4 v[116:119], v[130:131], off offset:1024
	global_load_dwordx4 v[88:91], v[40:41], off offset:2048
	global_load_dwordx4 v[104:107], v[128:129], off offset:2048
	global_load_dwordx4 v[120:123], v[130:131], off offset:2048
	global_load_dwordx4 v[92:95], v[40:41], off offset:3072
	global_load_dwordx4 v[108:111], v[128:129], off offset:3072
	global_load_dwordx4 v[124:127], v[130:131], off offset:3072
	s_waitcnt vmcnt(19)
	v_mul_f32_e32 v32, v29, v29
	v_mul_f32_e32 v33, v31, v31
	s_waitcnt vmcnt(18)
	v_mul_f32_e32 v34, v21, v21
	v_mul_f32_e32 v35, v23, v23
	s_waitcnt vmcnt(17)
	v_mul_f32_e32 v36, v13, v13
	v_mul_f32_e32 v37, v15, v15
	v_fmac_f32_e32 v32, v28, v28
	v_fmac_f32_e32 v33, v30, v30
	v_fmac_f32_e32 v34, v20, v20
	v_fmac_f32_e32 v35, v22, v22
	s_waitcnt vmcnt(16)
	v_mul_f32_e32 v38, v5, v5
	v_mul_f32_e32 v39, v7, v7
	v_fmac_f32_e32 v36, v12, v12
	v_fmac_f32_e32 v37, v14, v14
	v_add_f32_e32 v32, v32, v33
	v_add_f32_e32 v34, v34, v35
	v_fmac_f32_e32 v38, v4, v4
	v_fmac_f32_e32 v39, v6, v6
	v_add_f32_e32 v36, v36, v37
	v_add_f32_e32 v38, v38, v39
	v_add_f32_e32 v32, v32, v34
	v_add_f32_e32 v32, v32, v36
	v_add_f32_e32 v32, v32, v38
	s_waitcnt vmcnt(15)
	v_mul_f32_e32 v33, v25, v25
	v_mul_f32_e32 v52, v27, v27
	s_waitcnt vmcnt(14)
	v_mul_f32_e32 v35, v17, v17
	v_mul_f32_e32 v53, v19, v19
	s_waitcnt vmcnt(13)
	v_mul_f32_e32 v37, v9, v9
	v_mul_f32_e32 v54, v11, v11
	v_fmac_f32_e32 v33, v24, v24
	v_fmac_f32_e32 v52, v26, v26
	v_fmac_f32_e32 v35, v16, v16
	v_fmac_f32_e32 v53, v18, v18
	s_waitcnt vmcnt(12)
	v_mul_f32_e32 v39, v1, v1
	v_mul_f32_e32 v55, v3, v3
	v_fmac_f32_e32 v37, v8, v8
	v_fmac_f32_e32 v54, v10, v10
	v_add_f32_e32 v33, v33, v52
	v_add_f32_e32 v34, v35, v53
	v_fmac_f32_e32 v39, v0, v0
	v_fmac_f32_e32 v55, v2, v2
	v_add_f32_e32 v35, v37, v54
	v_add_f32_e32 v33, v33, v34
	v_add_f32_e32 v36, v39, v55
	v_add_f32_e32 v33, v33, v35
	v_add_f32_e32 v33, v33, v36
	ds_bpermute_b32 v34, v56, v32
	ds_bpermute_b32 v35, v56, v33
	s_waitcnt lgkmcnt(1)
	v_add_f32_e32 v32, v32, v34
	s_waitcnt lgkmcnt(0)
	v_add_f32_e32 v33, v33, v35
	ds_bpermute_b32 v34, v57, v32
	ds_bpermute_b32 v35, v57, v33
	s_waitcnt lgkmcnt(1)
	v_add_f32_e32 v32, v32, v34
	s_waitcnt lgkmcnt(0)
	v_add_f32_e32 v33, v33, v35
	ds_bpermute_b32 v34, v58, v32
	ds_bpermute_b32 v35, v58, v33
	s_waitcnt lgkmcnt(1)
	v_add_f32_e32 v32, v32, v34
	s_waitcnt lgkmcnt(0)
	v_add_f32_e32 v33, v33, v35
	ds_bpermute_b32 v34, v59, v32
	ds_bpermute_b32 v35, v59, v33
	s_waitcnt lgkmcnt(1)
	v_add_f32_e32 v32, v32, v34
	s_waitcnt lgkmcnt(0)
	v_add_f32_e32 v35, v33, v35
	ds_bpermute_b32 v34, v60, v32
	ds_bpermute_b32 v36, v60, v35
	s_waitcnt lgkmcnt(1)
	v_add_f32_e32 v32, v32, v34
	s_waitcnt lgkmcnt(0)
	v_add_f32_e32 v34, v35, v36
	ds_bpermute_b32 v33, v61, v32
	ds_bpermute_b32 v35, v61, v34
	s_waitcnt vmcnt(0)
	s_and_saveexec_b64 s[12:13], vcc
	s_cbranch_execz .LBB0_140
	s_waitcnt lgkmcnt(1)
	v_add_f32_e32 v36, v32, v33
	v_lshl_add_u64 v[32:33], v[48:49], 2, s[14:15]
	global_store_dword v[32:33], v36, off
	s_and_b64 exec, exec, s[0:1]
	s_cbranch_execz .LBB0_140
	s_waitcnt lgkmcnt(0)
	v_add_f32_e32 v34, v34, v35
	v_lshl_add_u64 v[32:33], s[94:95], 2, v[32:33]
	global_store_dword v[32:33], v34, off
; __device__ __forceinline__ unsigned cvt_pk_bf16(float lo, float hi) { unsigned r; asm volatile("v_cvt_pk_bf16_f32 %0, %1, %2" : "=v"(r) : "v"(lo), "v"(hi)); return r; }
; __device__ __forceinline__ void prenorm_rows(const float* src0, const float* src1, int row_lo, int row_hi, const float* g, const float* scale, float* SS, bf16_t* HB) {
;     ...
;         const f32x4* gp = (const f32x4*)g + lane;
;         const f32x4* sca = (const f32x4*)(scale + (size_t)mba * 9216) + lane; const f32x4* scb = (const f32x4*)(scale + (size_t)mbb * 9216) + lane;
;         u32x2* oa = (u32x2*)(HB + (size_t)row * D) + lane; u32x2* ob = (u32x2*)(HB + (size_t)rb * D) + lane;
; #pragma unroll
;         for (int j = 0; j < 4; ++j) { const f32x4 gj = gp[64 * j]; const f32x4 za = va[j] * gj * (sca[64 * j] + 1.0f), zb = vb[j] * gj * (scb[64 * j] + 1.0f);
;             u32x2 w; w.x = cvt_pk_bf16(za[0], za[1]); w.y = cvt_pk_bf16(za[2], za[3]); oa[64 * j] = w;
;             if (hasb) { w.x = cvt_pk_bf16(zb[0], zb[1]); w.y = cvt_pk_bf16(zb[2], zb[3]); ob[64 * j] = w; } }
.LBB0_140:
	s_or_b64 exec, exec, s[12:13]
	s_waitcnt lgkmcnt(0)
	v_lshlrev_b64 v[48:49], 11, v[48:49]
	v_lshlrev_b64 v[72:73], 11, v[50:51]
	v_lshl_add_u64 v[50:51], v[44:45], 0, v[48:49]
	v_lshl_add_u64 v[48:49], v[44:45], 0, v[72:73]
	v_pk_mul_f32 v[28:29], v[28:29], v[80:81]
	v_pk_add_f32 v[96:97], v[96:97], 1.0 op_sel_hi:[1,0]
	v_pk_mul_f32 v[30:31], v[30:31], v[82:83]
	v_pk_add_f32 v[98:99], v[98:99], 1.0 op_sel_hi:[1,0]
	v_pk_mul_f32 v[28:29], v[28:29], v[96:97]
	v_pk_mul_f32 v[30:31], v[30:31], v[98:99]
	v_cvt_pk_bf16_f32 v28, v28, v29
	s_nop 0
	v_cvt_pk_bf16_f32 v29, v30, v31
	global_store_dwordx2 v[50:51], v[28:29], off
	v_pk_mul_f32 v[20:21], v[20:21], v[84:85]
	v_pk_add_f32 v[100:101], v[100:101], 1.0 op_sel_hi:[1,0]
	v_pk_mul_f32 v[22:23], v[22:23], v[86:87]
	v_pk_add_f32 v[102:103], v[102:103], 1.0 op_sel_hi:[1,0]
	v_pk_mul_f32 v[20:21], v[20:21], v[100:101]
	v_pk_mul_f32 v[22:23], v[22:23], v[102:103]
	v_cvt_pk_bf16_f32 v20, v20, v21
	s_nop 0
	v_cvt_pk_bf16_f32 v21, v22, v23
	global_store_dwordx2 v[50:51], v[20:21], off offset:512
	v_pk_mul_f32 v[12:13], v[12:13], v[88:89]
	v_pk_add_f32 v[104:105], v[104:105], 1.0 op_sel_hi:[1,0]
	v_pk_mul_f32 v[14:15], v[14:15], v[90:91]
	v_pk_add_f32 v[106:107], v[106:107], 1.0 op_sel_hi:[1,0]
	v_pk_mul_f32 v[12:13], v[12:13], v[104:105]
	v_pk_mul_f32 v[14:15], v[14:15], v[106:107]
	v_cvt_pk_bf16_f32 v12, v12, v13
	s_nop 0
	v_cvt_pk_bf16_f32 v13, v14, v15
	global_store_dwordx2 v[50:51], v[12:13], off offset:1024
	v_pk_mul_f32 v[4:5], v[4:5], v[92:93]
	v_pk_add_f32 v[108:109], v[108:109], 1.0 op_sel_hi:[1,0]
	v_pk_mul_f32 v[6:7], v[6:7], v[94:95]
	v_pk_add_f32 v[110:111], v[110:111], 1.0 op_sel_hi:[1,0]
	v_pk_mul_f32 v[4:5], v[4:5], v[108:109]
	v_pk_mul_f32 v[6:7], v[6:7], v[110:111]
	v_cvt_pk_bf16_f32 v4, v4, v5
	s_nop 0
	v_cvt_pk_bf16_f32 v5, v6, v7
	global_store_dwordx2 v[50:51], v[4:5], off offset:1536
	s_and_saveexec_b64 s[12:13], s[0:1]
	s_cbranch_execz .LBB0_136
	v_pk_mul_f32 v[24:25], v[24:25], v[80:81]
	v_pk_add_f32 v[112:113], v[112:113], 1.0 op_sel_hi:[1,0]
	v_pk_mul_f32 v[26:27], v[26:27], v[82:83]
	v_pk_add_f32 v[114:115], v[114:115], 1.0 op_sel_hi:[1,0]
	v_pk_mul_f32 v[24:25], v[24:25], v[112:113]
	v_pk_mul_f32 v[26:27], v[26:27], v[114:115]
	v_cvt_pk_bf16_f32 v24, v24, v25
	s_nop 0
	v_cvt_pk_bf16_f32 v25, v26, v27
	global_store_dwordx2 v[48:49], v[24:25], off
	v_pk_mul_f32 v[16:17], v[16:17], v[84:85]
	v_pk_add_f32 v[116:117], v[116:117], 1.0 op_sel_hi:[1,0]
	v_pk_mul_f32 v[18:19], v[18:19], v[86:87]
	v_pk_add_f32 v[118:119], v[118:119], 1.0 op_sel_hi:[1,0]
	v_pk_mul_f32 v[16:17], v[16:17], v[116:117]
	v_pk_mul_f32 v[18:19], v[18:19], v[118:119]
	v_cvt_pk_bf16_f32 v16, v16, v17
	s_nop 0
	v_cvt_pk_bf16_f32 v17, v18, v19
	global_store_dwordx2 v[48:49], v[16:17], off offset:512
	v_pk_mul_f32 v[8:9], v[8:9], v[88:89]
	v_pk_add_f32 v[120:121], v[120:121], 1.0 op_sel_hi:[1,0]
	v_pk_mul_f32 v[10:11], v[10:11], v[90:91]
	v_pk_add_f32 v[122:123], v[122:123], 1.0 op_sel_hi:[1,0]
	v_pk_mul_f32 v[8:9], v[8:9], v[120:121]
	v_pk_mul_f32 v[10:11], v[10:11], v[122:123]
	v_cvt_pk_bf16_f32 v8, v8, v9
	s_nop 0
	v_cvt_pk_bf16_f32 v9, v10, v11
	global_store_dwordx2 v[48:49], v[8:9], off offset:1024
	v_pk_mul_f32 v[0:1], v[0:1], v[92:93]
	v_pk_add_f32 v[124:125], v[124:125], 1.0 op_sel_hi:[1,0]
	v_pk_mul_f32 v[2:3], v[2:3], v[94:95]
	v_pk_add_f32 v[126:127], v[126:127], 1.0 op_sel_hi:[1,0]
	v_pk_mul_f32 v[0:1], v[0:1], v[124:125]
	v_pk_mul_f32 v[2:3], v[2:3], v[126:127]
	v_cvt_pk_bf16_f32 v0, v0, v1
	s_nop 0
	v_cvt_pk_bf16_f32 v1, v2, v3
	global_store_dwordx2 v[48:49], v[0:1], off offset:1536
	s_branch .LBB0_136
